# k-loop: DMA block front-loaded into the first 4 MFMA slots after the barrier (was spread over 8)
# speedup vs baseline: 1.0091x; 1.0091x over previous
; #define MFMA(a, b, c) __builtin_amdgcn_mfma_f32_32x32x16_bf16((a), (b), (c), 0, 0, 0)
;     ...
;     auto issue_at = [&](int mm0, int nn0, int kt, int buf) {
;       char* lb = L0 + buf * BUFB;
; #pragma unroll
;       for (int i = 0; i < 4; ++i) {
;         const int seg = wv * 4 + i, row = seg * 8 + gl_row;
;         const int c = (lane & 7) ^ ((row >> 1) & 7);
;         const u16* ap = (kt < g.split) ? g.a0 + (size_t)(mm0 + row) * g.ld0 + kt * g.ks0 : g.a1 + (size_t)(mm0 + row) * g.ld1 + (kt - g.split) * 64;
;         __builtin_amdgcn_global_load_lds((const unsigned*)(ap + c * 8), (__attribute__((address_space(3))) unsigned*)(lb + seg * 1024 + lane * 16), 16, 0, 0);
;       }
; #pragma unroll
;       for (int i = 0; i < BN / 64; ++i) {
;         const int seg = wv * (BN / 64) + i, row = seg * 8 + gl_row;
;         const int c = (lane & 7) ^ ((row >> 1) & 7);
;         __builtin_amdgcn_global_load_lds((const unsigned*)(g.W + (size_t)(nn0 + row) * g.K + kt * 64 + c * 8),
;                                          (__attribute__((address_space(3))) unsigned*)(lb + 256 * 128 + seg * 1024 + lane * 16), 16, 0, 0);
;       }
;     ...
;     auto compute2 = [&](int buf) {
;       const char* lb = L0 + buf * BUFB;
; #pragma unroll
;       for (int ks = 0; ks < 4; ++ks) {
;         const int c = ks * 2 + hh;
;         bf16x8 wf[2], xf[MI];
; #pragma unroll
;         for (int j = 0; j < 2; ++j) { const int r = wn * 64 + j * 32 + l32; wf[j] = *(const bf16x8*)(lb + 256 * 128 + r * 128 + ((c ^ ((r >> 1) & 7)) << 4)); }
; #pragma unroll
;         for (int i = 0; i < MI; ++i) { const int r = wm * (MI * 32) + i * 32 + l32; xf[i] = *(const bf16x8*)(lb + r * 128 + ((c ^ ((r >> 1) & 7)) << 4)); }
; #pragma unroll
;         for (int i = 0; i < MI; ++i) {
;           acc[i][0] = MFMA(wf[0], xf[i], acc[i][0]);
;           acc[i][1] = MFMA(wf[1], xf[i], acc[i][1]);
;         }
;       }
.Lgemm_g1_798:
	v_add_u32_e32 v0, s14, v173
	v_add_u32_e32 v176, v0, v171
	v_add_u32_e32 v0, v0, v170
	s_waitcnt lgkmcnt(3)
	v_mfma_f32_32x32x16_bf16 v[114:129], v[224:227], v[232:235], v[114:129]
	ds_read_b128 v[200:203], v176 offset:32768
	v_mfma_f32_32x32x16_bf16 v[98:113], v[228:231], v[232:235], v[98:113]
	ds_read_b128 v[204:207], v176 offset:36864
	s_waitcnt lgkmcnt(4)
	v_mfma_f32_32x32x16_bf16 v[82:97], v[224:227], v[240:243], v[82:97]
	ds_read_b128 v[208:211], v0
	v_mfma_f32_32x32x16_bf16 v[66:81], v[228:231], v[240:243], v[66:81]
	ds_read_b128 v[212:215], v0 offset:4096
	s_waitcnt lgkmcnt(5)
	v_mfma_f32_32x32x16_bf16 v[50:65], v[224:227], v[244:247], v[50:65]
	ds_read_b128 v[216:219], v0 offset:8192
	v_mfma_f32_32x32x16_bf16 v[34:49], v[228:231], v[244:247], v[34:49]
	ds_read_b128 v[220:223], v0 offset:12288
	s_waitcnt lgkmcnt(6)
	v_mfma_f32_32x32x16_bf16 v[18:33], v[224:227], v[248:251], v[18:33]
	v_mfma_f32_32x32x16_bf16 v[2:17], v[228:231], v[248:251], v[2:17]
	v_add_u32_e32 v0, s14, v172
	v_add_u32_e32 v176, v0, v171
	v_add_u32_e32 v0, v0, v170
	s_waitcnt lgkmcnt(3)
	v_mfma_f32_32x32x16_bf16 v[114:129], v[200:203], v[208:211], v[114:129]
	ds_read_b128 v[224:227], v176 offset:32768
	v_mfma_f32_32x32x16_bf16 v[98:113], v[204:207], v[208:211], v[98:113]
	ds_read_b128 v[228:231], v176 offset:36864
	s_waitcnt lgkmcnt(4)
	v_mfma_f32_32x32x16_bf16 v[82:97], v[200:203], v[212:215], v[82:97]
	ds_read_b128 v[232:235], v0
	v_mfma_f32_32x32x16_bf16 v[66:81], v[204:207], v[212:215], v[66:81]
	ds_read_b128 v[240:243], v0 offset:4096
	s_waitcnt lgkmcnt(5)
	v_mfma_f32_32x32x16_bf16 v[50:65], v[200:203], v[216:219], v[50:65]
	ds_read_b128 v[244:247], v0 offset:8192
	v_mfma_f32_32x32x16_bf16 v[34:49], v[204:207], v[216:219], v[34:49]
	ds_read_b128 v[248:251], v0 offset:12288
	s_waitcnt lgkmcnt(6)
	v_mfma_f32_32x32x16_bf16 v[18:33], v[200:203], v[220:223], v[18:33]
	v_mfma_f32_32x32x16_bf16 v[2:17], v[204:207], v[220:223], v[2:17]
	s_waitcnt vmcnt(0)
	s_waitcnt vmcnt(0) lgkmcnt(0)
	s_barrier
	s_cbranch_scc1 .Lgemm_exit_798
	s_and_b32 s14, s11, 0x10000
	s_xor_b32 s15, s14, 0x10000
	s_add_i32 s15, s15, 0
	s_add_i32 s14, s14, 0
	v_add_u32_e32 v0, s14, v175
	v_add_u32_e32 v176, v0, v171
	v_add_u32_e32 v0, v0, v170
	ds_read_b128 v[200:203], v176 offset:32768
	ds_read_b128 v[204:207], v176 offset:36864
	ds_read_b128 v[208:211], v0
	ds_read_b128 v[212:215], v0 offset:4096
	ds_read_b128 v[216:219], v0 offset:8192
	ds_read_b128 v[220:223], v0 offset:12288
	v_mfma_f32_32x32x16_bf16 v[114:129], v[224:227], v[232:235], v[114:129]
	s_add_i32 s64, s15, 0x8000
	s_add_i32 m0, s15, s60
	v_lshl_add_u64 v[176:177], v[152:153], 0, s[2:3]
	global_load_lds_dwordx4 v[176:177], off
	s_add_i32 m0, s15, s61
	v_lshl_add_u64 v[176:177], v[150:151], 0, s[2:3]
	global_load_lds_dwordx4 v[176:177], off
	v_mfma_f32_32x32x16_bf16 v[98:113], v[228:231], v[232:235], v[98:113]
	s_add_i32 m0, s15, s62
	v_lshl_add_u64 v[176:177], v[148:149], 0, s[2:3]
	global_load_lds_dwordx4 v[176:177], off
	s_add_i32 m0, s15, s63
	v_lshl_add_u64 v[176:177], v[146:147], 0, s[2:3]
	global_load_lds_dwordx4 v[176:177], off
	s_add_i32 m0, s64, s60
	v_mfma_f32_32x32x16_bf16 v[82:97], v[224:227], v[240:243], v[82:97]
	v_lshl_add_u64 v[176:177], v[144:145], 0, s[2:3]
	global_load_lds_dwordx4 v[176:177], off
	s_add_i32 m0, s64, s61
	v_lshl_add_u64 v[176:177], v[142:143], 0, s[2:3]
	global_load_lds_dwordx4 v[176:177], off
	s_add_i32 m0, s64, s62
	v_lshl_add_u64 v[176:177], v[140:141], 0, s[2:3]
	v_mfma_f32_32x32x16_bf16 v[66:81], v[228:231], v[240:243], v[66:81]
	global_load_lds_dwordx4 v[176:177], off
	s_add_i32 m0, s64, s63
	v_lshl_add_u64 v[176:177], v[138:139], 0, s[2:3]
	global_load_lds_dwordx4 v[176:177], off
	v_mfma_f32_32x32x16_bf16 v[50:65], v[224:227], v[244:247], v[50:65]
	v_mfma_f32_32x32x16_bf16 v[34:49], v[228:231], v[244:247], v[34:49]
	v_mfma_f32_32x32x16_bf16 v[18:33], v[224:227], v[248:251], v[18:33]
	v_mfma_f32_32x32x16_bf16 v[2:17], v[228:231], v[248:251], v[2:17]
	s_branch .Lgemm_rot_798

; #define MFMA(a, b, c) __builtin_amdgcn_mfma_f32_32x32x16_bf16((a), (b), (c), 0, 0, 0)
;     ...
;     auto issue_at = [&](int mm0, int nn0, int kt, int buf) {
;       char* lb = L0 + buf * BUFB;
; #pragma unroll
;       for (int i = 0; i < 4; ++i) {
;         const int seg = wv * 4 + i, row = seg * 8 + gl_row;
;         const int c = (lane & 7) ^ ((row >> 1) & 7);
;         const u16* ap = (kt < g.split) ? g.a0 + (size_t)(mm0 + row) * g.ld0 + kt * g.ks0 : g.a1 + (size_t)(mm0 + row) * g.ld1 + (kt - g.split) * 64;
;         __builtin_amdgcn_global_load_lds((const unsigned*)(ap + c * 8), (__attribute__((address_space(3))) unsigned*)(lb + seg * 1024 + lane * 16), 16, 0, 0);
;       }
; #pragma unroll
;       for (int i = 0; i < BN / 64; ++i) {
;         const int seg = wv * (BN / 64) + i, row = seg * 8 + gl_row;
;         const int c = (lane & 7) ^ ((row >> 1) & 7);
;         __builtin_amdgcn_global_load_lds((const unsigned*)(g.W + (size_t)(nn0 + row) * g.K + kt * 64 + c * 8),
;                                          (__attribute__((address_space(3))) unsigned*)(lb + 256 * 128 + seg * 1024 + lane * 16), 16, 0, 0);
;       }
;     ...
;     auto compute2 = [&](int buf) {
;       const char* lb = L0 + buf * BUFB;
; #pragma unroll
;       for (int ks = 0; ks < 4; ++ks) {
;         const int c = ks * 2 + hh;
;         bf16x8 wf[2], xf[MI];
; #pragma unroll
;         for (int j = 0; j < 2; ++j) { const int r = wn * 64 + j * 32 + l32; wf[j] = *(const bf16x8*)(lb + 256 * 128 + r * 128 + ((c ^ ((r >> 1) & 7)) << 4)); }
; #pragma unroll
;         for (int i = 0; i < MI; ++i) { const int r = wm * (MI * 32) + i * 32 + l32; xf[i] = *(const bf16x8*)(lb + r * 128 + ((c ^ ((r >> 1) & 7)) << 4)); }
; #pragma unroll
;         for (int i = 0; i < MI; ++i) {
;           acc[i][0] = MFMA(wf[0], xf[i], acc[i][0]);
;           acc[i][1] = MFMA(wf[1], xf[i], acc[i][1]);
;         }
;       }
.Lgemm_g1_1274:
	v_add_u32_e32 v233, s59, v199
	v_add_u32_e32 v230, v233, v175
	v_add_u32_e32 v234, v233, v174
	s_waitcnt lgkmcnt(3)
	v_mfma_f32_32x32x16_bf16 v[114:129], v[240:243], v[248:251], v[114:129]
	ds_read_b128 v[202:205], v230 offset:32768
	v_mfma_f32_32x32x16_bf16 v[98:113], v[244:247], v[248:251], v[98:113]
	ds_read_b128 v[206:209], v230 offset:36864
	s_waitcnt lgkmcnt(4)
	v_mfma_f32_32x32x16_bf16 v[82:97], v[240:243], v[214:217], v[82:97]
	ds_read_b128 v[210:213], v234
	v_mfma_f32_32x32x16_bf16 v[66:81], v[244:247], v[214:217], v[66:81]
	ds_read_b128 v[214:217], v234 offset:4096
	s_waitcnt lgkmcnt(5)
	v_mfma_f32_32x32x16_bf16 v[50:65], v[240:243], v[218:221], v[50:65]
	v_mfma_f32_32x32x16_bf16 v[34:49], v[244:247], v[218:221], v[34:49]
	ds_read_b128 v[218:221], v234 offset:8192
	s_waitcnt lgkmcnt(5)
	v_mfma_f32_32x32x16_bf16 v[18:33], v[240:243], v[222:225], v[18:33]
	v_mfma_f32_32x32x16_bf16 v[2:17], v[244:247], v[222:225], v[2:17]
	ds_read_b128 v[222:225], v234 offset:12288
	v_add_u32_e32 v233, s59, v176
	v_add_u32_e32 v230, v233, v175
	v_add_u32_e32 v234, v233, v174
	s_waitcnt lgkmcnt(3)
	v_mfma_f32_32x32x16_bf16 v[114:129], v[202:205], v[210:213], v[114:129]
	ds_read_b128 v[240:243], v230 offset:32768
	v_mfma_f32_32x32x16_bf16 v[98:113], v[206:209], v[210:213], v[98:113]
	ds_read_b128 v[244:247], v230 offset:36864
	s_waitcnt lgkmcnt(4)
	v_mfma_f32_32x32x16_bf16 v[82:97], v[202:205], v[214:217], v[82:97]
	ds_read_b128 v[248:251], v234
	v_mfma_f32_32x32x16_bf16 v[66:81], v[206:209], v[214:217], v[66:81]
	ds_read_b128 v[214:217], v234 offset:4096
	s_waitcnt lgkmcnt(5)
	v_mfma_f32_32x32x16_bf16 v[50:65], v[202:205], v[218:221], v[50:65]
	v_mfma_f32_32x32x16_bf16 v[34:49], v[206:209], v[218:221], v[34:49]
	ds_read_b128 v[218:221], v234 offset:8192
	s_waitcnt lgkmcnt(5)
	v_mfma_f32_32x32x16_bf16 v[18:33], v[202:205], v[222:225], v[18:33]
	v_mfma_f32_32x32x16_bf16 v[2:17], v[206:209], v[222:225], v[2:17]
	ds_read_b128 v[222:225], v234 offset:12288
	s_waitcnt vmcnt(0)
	s_waitcnt vmcnt(0) lgkmcnt(0)
	s_barrier
	s_cbranch_scc1 .Lgemm_exit_1274
	s_and_b32 s59, s56, 0x10000
	s_xor_b32 s60, s59, 0x10000
	s_add_i32 s57, s58, 1
	s_add_i32 s60, s60, 0
	s_cmp_lt_u32 s58, 21
	s_cselect_b64 vcc, -1, 0
	v_add_u32_e32 v233, s59, v201
	v_add_u32_e32 v230, v233, v175
	v_add_u32_e32 v234, v233, v174
	ds_read_b128 v[202:205], v230 offset:32768
	ds_read_b128 v[206:209], v230 offset:36864
	ds_read_b128 v[210:213], v234
	v_mfma_f32_32x32x16_bf16 v[114:129], v[240:243], v[248:251], v[114:129]
	s_add_i32 s66, s60, 0x8000
	v_lshl_add_u64 v[226:227], v[160:161], 0, s[2:3]
	v_lshl_add_u64 v[228:229], v[144:145], 0, s[2:3]
	v_cndmask_b32_e32 v227, v229, v227, vcc
	v_cndmask_b32_e32 v226, v228, v226, vcc
	v_lshl_add_u64 v[226:227], v[0:1], 1, v[226:227]
	s_add_i32 m0, s60, s62
	v_lshl_add_u64 v[228:229], v[142:143], 0, s[2:3]
	global_load_lds_dwordx4 v[226:227], off
	v_lshl_add_u64 v[226:227], v[158:159], 0, s[2:3]
	v_cndmask_b32_e32 v227, v229, v227, vcc
	v_mfma_f32_32x32x16_bf16 v[98:113], v[244:247], v[248:251], v[98:113]
	v_cndmask_b32_e32 v226, v228, v226, vcc
	v_lshl_add_u64 v[226:227], v[130:131], 1, v[226:227]
	s_add_i32 m0, s60, s63
	v_lshl_add_u64 v[228:229], v[140:141], 0, s[2:3]
	global_load_lds_dwordx4 v[226:227], off
	v_lshl_add_u64 v[226:227], v[156:157], 0, s[2:3]
	v_cndmask_b32_e32 v227, v229, v227, vcc
	v_cndmask_b32_e32 v226, v228, v226, vcc
	v_lshl_add_u64 v[226:227], v[132:133], 1, v[226:227]
	s_add_i32 m0, s60, s64
	v_lshl_add_u64 v[228:229], v[138:139], 0, s[2:3]
	v_mfma_f32_32x32x16_bf16 v[82:97], v[240:243], v[214:217], v[82:97]
	global_load_lds_dwordx4 v[226:227], off
	v_lshl_add_u64 v[226:227], v[154:155], 0, s[2:3]
	v_cndmask_b32_e32 v226, v228, v226, vcc
	v_cndmask_b32_e32 v227, v229, v227, vcc
	s_add_i32 m0, s60, s65
	v_lshl_add_u64 v[226:227], v[134:135], 1, v[226:227]
	global_load_lds_dwordx4 v[226:227], off
	s_add_i32 m0, s66, s62
	v_lshl_add_u64 v[226:227], v[146:147], 0, s[2:3]
	global_load_lds_dwordx4 v[226:227], off
	s_add_i32 m0, s66, s63
	v_mfma_f32_32x32x16_bf16 v[66:81], v[244:247], v[214:217], v[66:81]
	ds_read_b128 v[214:217], v234 offset:4096
	v_lshl_add_u64 v[226:227], v[148:149], 0, s[2:3]
	global_load_lds_dwordx4 v[226:227], off
	s_add_i32 m0, s66, s64
	v_lshl_add_u64 v[226:227], v[150:151], 0, s[2:3]
	global_load_lds_dwordx4 v[226:227], off
	v_lshl_add_u64 v[226:227], v[152:153], 0, s[2:3]
	s_add_i32 m0, s66, s65
	s_add_i32 s58, s59, 0
	global_load_lds_dwordx4 v[226:227], off
	v_mfma_f32_32x32x16_bf16 v[50:65], v[240:243], v[218:221], v[50:65]
	v_mfma_f32_32x32x16_bf16 v[34:49], v[244:247], v[218:221], v[34:49]
	ds_read_b128 v[218:221], v234 offset:8192
	v_mfma_f32_32x32x16_bf16 v[18:33], v[240:243], v[222:225], v[18:33]
	v_mfma_f32_32x32x16_bf16 v[2:17], v[244:247], v[222:225], v[2:17]
	ds_read_b128 v[222:225], v234 offset:12288
	s_branch .Lgemm_rot_1274

; #define MFMA(a, b, c) __builtin_amdgcn_mfma_f32_32x32x16_bf16((a), (b), (c), 0, 0, 0)
;     ...
;     auto issue_at = [&](int mm0, int nn0, int kt, int buf) {
;       char* lb = L0 + buf * BUFB;
; #pragma unroll
;       for (int i = 0; i < 4; ++i) {
;         const int seg = wv * 4 + i, row = seg * 8 + gl_row;
;         const int c = (lane & 7) ^ ((row >> 1) & 7);
;         const u16* ap = (kt < g.split) ? g.a0 + (size_t)(mm0 + row) * g.ld0 + kt * g.ks0 : g.a1 + (size_t)(mm0 + row) * g.ld1 + (kt - g.split) * 64;
;         __builtin_amdgcn_global_load_lds((const unsigned*)(ap + c * 8), (__attribute__((address_space(3))) unsigned*)(lb + seg * 1024 + lane * 16), 16, 0, 0);
;       }
; #pragma unroll
;       for (int i = 0; i < BN / 64; ++i) {
;         const int seg = wv * (BN / 64) + i, row = seg * 8 + gl_row;
;         const int c = (lane & 7) ^ ((row >> 1) & 7);
;         __builtin_amdgcn_global_load_lds((const unsigned*)(g.W + (size_t)(nn0 + row) * g.K + kt * 64 + c * 8),
;                                          (__attribute__((address_space(3))) unsigned*)(lb + 256 * 128 + seg * 1024 + lane * 16), 16, 0, 0);
;       }
;     ...
;     auto compute2 = [&](int buf) {
;       const char* lb = L0 + buf * BUFB;
; #pragma unroll
;       for (int ks = 0; ks < 4; ++ks) {
;         const int c = ks * 2 + hh;
;         bf16x8 wf[2], xf[MI];
; #pragma unroll
;         for (int j = 0; j < 2; ++j) { const int r = wn * 64 + j * 32 + l32; wf[j] = *(const bf16x8*)(lb + 256 * 128 + r * 128 + ((c ^ ((r >> 1) & 7)) << 4)); }
; #pragma unroll
;         for (int i = 0; i < MI; ++i) { const int r = wm * (MI * 32) + i * 32 + l32; xf[i] = *(const bf16x8*)(lb + r * 128 + ((c ^ ((r >> 1) & 7)) << 4)); }
; #pragma unroll
;         for (int i = 0; i < MI; ++i) {
;           acc[i][0] = MFMA(wf[0], xf[i], acc[i][0]);
;           acc[i][1] = MFMA(wf[1], xf[i], acc[i][1]);
;         }
;       }
.Lgemm_g1_1371:
	v_add_u32_e32 v0, s17, v172
	v_add_u32_e32 v175, v0, v170
	v_add_u32_e32 v0, v0, v169
	s_waitcnt lgkmcnt(3)
	v_mfma_f32_32x32x16_bf16 v[114:129], v[224:227], v[232:235], v[114:129]
	ds_read_b128 v[200:203], v175 offset:32768
	v_mfma_f32_32x32x16_bf16 v[98:113], v[228:231], v[232:235], v[98:113]
	ds_read_b128 v[204:207], v175 offset:36864
	s_waitcnt lgkmcnt(4)
	v_mfma_f32_32x32x16_bf16 v[82:97], v[224:227], v[240:243], v[82:97]
	ds_read_b128 v[208:211], v0
	v_mfma_f32_32x32x16_bf16 v[66:81], v[228:231], v[240:243], v[66:81]
	ds_read_b128 v[212:215], v0 offset:4096
	s_waitcnt lgkmcnt(5)
	v_mfma_f32_32x32x16_bf16 v[50:65], v[224:227], v[244:247], v[50:65]
	ds_read_b128 v[216:219], v0 offset:8192
	v_mfma_f32_32x32x16_bf16 v[34:49], v[228:231], v[244:247], v[34:49]
	ds_read_b128 v[220:223], v0 offset:12288
	s_waitcnt lgkmcnt(6)
	v_mfma_f32_32x32x16_bf16 v[18:33], v[224:227], v[248:251], v[18:33]
	v_mfma_f32_32x32x16_bf16 v[2:17], v[228:231], v[248:251], v[2:17]
	v_add_u32_e32 v0, s17, v171
	v_add_u32_e32 v175, v0, v170
	v_add_u32_e32 v0, v0, v169
	s_waitcnt lgkmcnt(3)
	v_mfma_f32_32x32x16_bf16 v[114:129], v[200:203], v[208:211], v[114:129]
	ds_read_b128 v[224:227], v175 offset:32768
	v_mfma_f32_32x32x16_bf16 v[98:113], v[204:207], v[208:211], v[98:113]
	ds_read_b128 v[228:231], v175 offset:36864
	s_waitcnt lgkmcnt(4)
	v_mfma_f32_32x32x16_bf16 v[82:97], v[200:203], v[212:215], v[82:97]
	ds_read_b128 v[232:235], v0
	v_mfma_f32_32x32x16_bf16 v[66:81], v[204:207], v[212:215], v[66:81]
	ds_read_b128 v[240:243], v0 offset:4096
	s_waitcnt lgkmcnt(5)
	v_mfma_f32_32x32x16_bf16 v[50:65], v[200:203], v[216:219], v[50:65]
	ds_read_b128 v[244:247], v0 offset:8192
	v_mfma_f32_32x32x16_bf16 v[34:49], v[204:207], v[216:219], v[34:49]
	ds_read_b128 v[248:251], v0 offset:12288
	s_waitcnt lgkmcnt(6)
	v_mfma_f32_32x32x16_bf16 v[18:33], v[200:203], v[220:223], v[18:33]
	v_mfma_f32_32x32x16_bf16 v[2:17], v[204:207], v[220:223], v[2:17]
	s_waitcnt vmcnt(0)
	s_waitcnt vmcnt(0) lgkmcnt(0)
	s_barrier
	s_cbranch_scc1 .Lgemm_exit_1371
	s_and_b32 s17, s16, 0x10000
	s_xor_b32 s43, s17, 0x10000
	s_add_i32 s43, s43, 0
	s_add_i32 s17, s17, 0
	v_add_u32_e32 v0, s17, v174
	v_add_u32_e32 v175, v0, v170
	v_add_u32_e32 v0, v0, v169
	ds_read_b128 v[200:203], v175 offset:32768
	ds_read_b128 v[204:207], v175 offset:36864
	ds_read_b128 v[208:211], v0
	ds_read_b128 v[212:215], v0 offset:4096
	ds_read_b128 v[216:219], v0 offset:8192
	ds_read_b128 v[220:223], v0 offset:12288
	v_mfma_f32_32x32x16_bf16 v[114:129], v[224:227], v[232:235], v[114:129]
	s_add_i32 s64, s43, 0x8000
	s_add_i32 m0, s43, s60
	v_lshl_add_u64 v[176:177], v[152:153], 0, s[10:11]
	global_load_lds_dwordx4 v[176:177], off
	s_add_i32 m0, s43, s61
	v_lshl_add_u64 v[176:177], v[150:151], 0, s[10:11]
	global_load_lds_dwordx4 v[176:177], off
	v_mfma_f32_32x32x16_bf16 v[98:113], v[228:231], v[232:235], v[98:113]
	s_add_i32 m0, s43, s62
	v_lshl_add_u64 v[176:177], v[148:149], 0, s[10:11]
	global_load_lds_dwordx4 v[176:177], off
	s_add_i32 m0, s43, s63
	v_lshl_add_u64 v[176:177], v[146:147], 0, s[10:11]
	global_load_lds_dwordx4 v[176:177], off
	s_add_i32 m0, s64, s60
	v_mfma_f32_32x32x16_bf16 v[82:97], v[224:227], v[240:243], v[82:97]
	v_lshl_add_u64 v[176:177], v[144:145], 0, s[10:11]
	global_load_lds_dwordx4 v[176:177], off
	s_add_i32 m0, s64, s61
	v_lshl_add_u64 v[176:177], v[142:143], 0, s[10:11]
	global_load_lds_dwordx4 v[176:177], off
	s_add_i32 m0, s64, s62
	v_lshl_add_u64 v[176:177], v[140:141], 0, s[10:11]
	v_mfma_f32_32x32x16_bf16 v[66:81], v[228:231], v[240:243], v[66:81]
	global_load_lds_dwordx4 v[176:177], off
	s_add_i32 m0, s64, s63
	v_lshl_add_u64 v[176:177], v[138:139], 0, s[10:11]
	global_load_lds_dwordx4 v[176:177], off
	v_mfma_f32_32x32x16_bf16 v[50:65], v[224:227], v[244:247], v[50:65]
	v_mfma_f32_32x32x16_bf16 v[34:49], v[228:231], v[244:247], v[34:49]
	v_mfma_f32_32x32x16_bf16 v[18:33], v[224:227], v[248:251], v[18:33]
	v_mfma_f32_32x32x16_bf16 v[2:17], v[228:231], v[248:251], v[2:17]
	s_branch .Lgemm_rot_1371
